# EpiRes epilogues (P2 P9 P11): the second vmcnt(0), which after the earlier wait move only drained the first stores, is removed
# speedup vs baseline: 1.0193x; 1.0009x over previous
; __device__ __forceinline__ unsigned cvtpk(float lo, float hi) { f32x2_t v = {lo, hi}; bf16x2_t b = __builtin_convertvector(v, bf16x2_t); return __builtin_bit_cast(unsigned, b); }
; __device__ __forceinline__ float bflo(unsigned u) { return __uint_as_float(u << 16); }
; __device__ __forceinline__ float bfhi(unsigned u) { return __uint_as_float(u & 0xffff0000u); }
;     __device__ __forceinline__ void operator()(const AccT& acc, const Unit& u, int wr, int wc, int fr, int fq) const {
;     ...
;             for (int m = 0; m < 4; ++m) { const int row = row0 + ai * 128 + m * 16; bf16_t* bp = bp0 + (size_t)(ai * 128 + m * 16) * DM; float q = 0.f;
; #pragma unroll
;                 for (int bj = 0; bj < 2; ++bj) { const u32x4 h4 = hv[ai][m][bj];
;                     f32x4 v0 = {bflo(h4.x), bfhi(h4.x), bflo(h4.y), bfhi(h4.y)}, v1 = {bflo(h4.z), bfhi(h4.z), bflo(h4.w), bfhi(h4.w)};
;                     v0 = v0 + acc[ai][bj][m][0] * c; v1 = v1 + acc[ai][bj][m][1] * c;
;                     q += ((v0[0] * v0[0] + v0[1] * v0[1]) + (v0[2] * v0[2] + v0[3] * v0[3])) + ((v1[0] * v1[0] + v1[1] * v1[1]) + (v1[2] * v1[2] + v1[3] * v1[3]));
;                     u32x4 w; w.x = cvtpk(v0[0], v0[1]); w.y = cvtpk(v0[2], v0[3]); w.z = cvtpk(v1[0], v1[1]); w.w = cvtpk(v1[2], v1[3]); *(u32x4*)(bp + bj * 128) = w; }
;                 q = xsum_16_32(q);
;                 if (fq == 0) ssn[(size_t)row * 16 + u.pn * 4 + wc] = q; }
.LBB0_304:
	s_or_b64 exec, exec, s[28:29]
	v_lshlrev_b32_e32 v54, 16, v46
	v_and_b32_e32 v55, 0xffff0000, v46
	v_lshlrev_b32_e32 v46, 16, v47
	v_and_b32_e32 v47, 0xffff0000, v47
	v_lshlrev_b32_e32 v56, 16, v48
	v_and_b32_e32 v57, 0xffff0000, v48
	v_lshlrev_b32_e32 v48, 16, v49
	v_and_b32_e32 v49, 0xffff0000, v49
	v_pk_add_f32 v[60:61], v[168:169], v[46:47]
	v_pk_add_f32 v[46:47], v[166:167], v[54:55]
	v_pk_add_f32 v[54:55], v[164:165], v[48:49]
	v_pk_add_f32 v[48:49], v[162:163], v[56:57]
	v_mul_f32_e32 v56, v47, v47
	v_mul_f32_e32 v57, v61, v61
	v_fmac_f32_e32 v56, v46, v46
	v_fmac_f32_e32 v57, v60, v60
	s_mov_b64 s[14:15], 0x10000
	v_add_f32_e32 v56, v56, v57
	v_mul_f32_e32 v57, v49, v49
	v_lshl_add_u64 v[50:51], v[152:153], 0, s[14:15]
	v_fmac_f32_e32 v57, v48, v48
	v_cvt_pk_bf16_f32 v46, v46, v47
	v_cvt_pk_bf16_f32 v47, v60, v61
	v_cvt_pk_bf16_f32 v48, v48, v49
	v_cvt_pk_bf16_f32 v49, v54, v55
	global_store_dwordx4 v[50:51], v[46:49], off
	v_mul_f32_e32 v162, v55, v55
	v_fmac_f32_e32 v162, v54, v54
	v_lshlrev_b32_e32 v46, 16, v42
	v_and_b32_e32 v47, 0xffff0000, v42
	v_lshlrev_b32_e32 v42, 16, v43
	v_and_b32_e32 v43, 0xffff0000, v43
	v_lshlrev_b32_e32 v48, 16, v44
	v_and_b32_e32 v49, 0xffff0000, v44
	v_lshlrev_b32_e32 v44, 16, v45
	v_and_b32_e32 v45, 0xffff0000, v45
	v_pk_add_f32 v[50:51], v[160:161], v[42:43]
	v_pk_add_f32 v[42:43], v[158:159], v[46:47]
	v_pk_add_f32 v[46:47], v[156:157], v[44:45]
	v_pk_add_f32 v[44:45], v[154:155], v[48:49]
	v_mul_f32_e32 v48, v43, v43
	v_mul_f32_e32 v49, v51, v51
	v_fmac_f32_e32 v48, v42, v42
	v_fmac_f32_e32 v49, v50, v50
	v_add_f32_e32 v48, v48, v49
	v_mul_f32_e32 v49, v45, v45
	v_mul_f32_e32 v54, v47, v47
	v_fmac_f32_e32 v49, v44, v44
	v_fmac_f32_e32 v54, v46, v46
	v_add_f32_e32 v57, v57, v162
	v_add_f32_e32 v49, v49, v54
	s_mov_b64 s[14:15], 0x10100
	v_add_f32_e32 v56, v56, v57
	v_add_f32_e32 v48, v48, v49
	v_lshl_add_u64 v[52:53], v[152:153], 0, s[14:15]
	v_add_f32_e32 v48, v56, v48
	v_cvt_pk_bf16_f32 v42, v42, v43
	v_cvt_pk_bf16_f32 v43, v50, v51
	v_cvt_pk_bf16_f32 v44, v44, v45
	v_cvt_pk_bf16_f32 v45, v46, v47
	global_store_dwordx4 v[52:53], v[42:45], off
	s_nop 1
	v_mov_b32_e32 v42, v48
	s_nop 1
	v_permlane16_swap_b32_e32 v48, v42
	v_add_f32_e32 v42, v48, v42
	v_mov_b32_e32 v43, v42
	s_nop 1
	v_permlane32_swap_b32_e32 v42, v43
	s_and_saveexec_b64 s[28:29], s[40:41]
	s_cbranch_execz .LBB0_306
	v_or_b32_e32 v44, 32, v206
	v_ashrrev_i32_e32 v45, 31, v44
	v_add_f32_e32 v46, v42, v43
	v_lshlrev_b64 v[42:43], 6, v[44:45]
	v_lshl_add_u64 v[42:43], s[22:23], 0, v[42:43]
	v_lshl_add_u64 v[42:43], s[0:1], 2, v[42:43]
	s_lshl_b32 s80, s30, 2
	v_lshl_add_u64 v[42:43], v[42:43], 0, s[80:81]
	global_store_dword v[42:43], v46, off

; __device__ __forceinline__ unsigned cvtpk(float lo, float hi) { f32x2_t v = {lo, hi}; bf16x2_t b = __builtin_convertvector(v, bf16x2_t); return __builtin_bit_cast(unsigned, b); }
; __device__ __forceinline__ float bflo(unsigned u) { return __uint_as_float(u << 16); }
; __device__ __forceinline__ float bfhi(unsigned u) { return __uint_as_float(u & 0xffff0000u); }
;     __device__ __forceinline__ void operator()(const AccT& acc, const Unit& u, int wr, int wc, int fr, int fq) const {
;     ...
;             for (int m = 0; m < 4; ++m) { const int row = row0 + ai * 128 + m * 16; bf16_t* bp = bp0 + (size_t)(ai * 128 + m * 16) * DM; float q = 0.f;
; #pragma unroll
;                 for (int bj = 0; bj < 2; ++bj) { const u32x4 h4 = hv[ai][m][bj];
;                     f32x4 v0 = {bflo(h4.x), bfhi(h4.x), bflo(h4.y), bfhi(h4.y)}, v1 = {bflo(h4.z), bfhi(h4.z), bflo(h4.w), bfhi(h4.w)};
;                     v0 = v0 + acc[ai][bj][m][0] * c; v1 = v1 + acc[ai][bj][m][1] * c;
;                     q += ((v0[0] * v0[0] + v0[1] * v0[1]) + (v0[2] * v0[2] + v0[3] * v0[3])) + ((v1[0] * v1[0] + v1[1] * v1[1]) + (v1[2] * v1[2] + v1[3] * v1[3]));
;                     u32x4 w; w.x = cvtpk(v0[0], v0[1]); w.y = cvtpk(v0[2], v0[3]); w.z = cvtpk(v1[0], v1[1]); w.w = cvtpk(v1[2], v1[3]); *(u32x4*)(bp + bj * 128) = w; }
;                 q = xsum_16_32(q);
;                 if (fq == 0) ssn[(size_t)row * 16 + u.pn * 4 + wc] = q; }
.LBB0_1784:
	s_or_b64 exec, exec, s[28:29]
	v_lshlrev_b32_e32 v102, 16, v174
	v_and_b32_e32 v103, 0xffff0000, v174
	v_lshlrev_b32_e32 v104, 16, v175
	v_and_b32_e32 v105, 0xffff0000, v175
	v_lshlrev_b32_e32 v106, 16, v176
	v_and_b32_e32 v107, 0xffff0000, v176
	v_lshlrev_b32_e32 v108, 16, v177
	v_and_b32_e32 v109, 0xffff0000, v177
	v_pk_add_f32 v[96:97], v[96:97], v[104:105]
	v_pk_add_f32 v[94:95], v[94:95], v[102:103]
	v_pk_add_f32 v[102:103], v[92:93], v[108:109]
	v_pk_add_f32 v[92:93], v[90:91], v[106:107]
	v_mul_f32_e32 v90, v95, v95
	v_mul_f32_e32 v91, v97, v97
	v_fmac_f32_e32 v90, v94, v94
	v_fmac_f32_e32 v91, v96, v96
	v_add_f32_e32 v90, v90, v91
	v_mul_f32_e32 v91, v93, v93
	v_mul_f32_e32 v104, v103, v103
	v_fmac_f32_e32 v91, v92, v92
	v_fmac_f32_e32 v104, v102, v102
	s_mov_b64 s[14:15], 0x10000
	v_add_f32_e32 v91, v91, v104
	v_lshl_add_u64 v[98:99], v[212:213], 0, s[14:15]
	v_add_f32_e32 v104, v90, v91
	v_cvt_pk_bf16_f32 v90, v94, v95
	v_cvt_pk_bf16_f32 v91, v96, v97
	v_cvt_pk_bf16_f32 v92, v92, v93
	v_cvt_pk_bf16_f32 v93, v102, v103
	global_store_dwordx4 v[98:99], v[90:93], off
	v_lshlrev_b32_e32 v94, 16, v172
	v_and_b32_e32 v95, 0xffff0000, v172
	v_lshlrev_b32_e32 v90, 16, v170
	v_and_b32_e32 v91, 0xffff0000, v170
	v_lshlrev_b32_e32 v92, 16, v171
	v_and_b32_e32 v93, 0xffff0000, v171
	v_lshlrev_b32_e32 v96, 16, v173
	v_and_b32_e32 v97, 0xffff0000, v173
	v_pk_add_f32 v[88:89], v[88:89], v[92:93]
	v_pk_add_f32 v[86:87], v[86:87], v[90:91]
	v_pk_add_f32 v[90:91], v[84:85], v[96:97]
	v_pk_add_f32 v[84:85], v[82:83], v[94:95]
	v_mul_f32_e32 v82, v87, v87
	v_mul_f32_e32 v83, v89, v89
	v_fmac_f32_e32 v82, v86, v86
	v_fmac_f32_e32 v83, v88, v88
	v_add_f32_e32 v82, v82, v83
	v_mul_f32_e32 v83, v85, v85
	v_mul_f32_e32 v92, v91, v91
	v_fmac_f32_e32 v83, v84, v84
	v_fmac_f32_e32 v92, v90, v90
	v_add_f32_e32 v83, v83, v92
	s_mov_b64 s[14:15], 0x10100
	v_add_f32_e32 v82, v82, v83
	v_lshl_add_u64 v[100:101], v[212:213], 0, s[14:15]
	v_add_f32_e32 v92, v104, v82
	v_cvt_pk_bf16_f32 v82, v86, v87
	v_cvt_pk_bf16_f32 v83, v88, v89
	v_cvt_pk_bf16_f32 v84, v84, v85
	v_cvt_pk_bf16_f32 v85, v90, v91
	global_store_dwordx4 v[100:101], v[82:85], off
	s_nop 1
	v_mov_b32_e32 v82, v92
	s_nop 1
	v_permlane16_swap_b32_e32 v92, v82
	v_add_f32_e32 v82, v92, v82
	v_mov_b32_e32 v83, v82
	s_nop 1
	v_permlane32_swap_b32_e32 v82, v83
	s_and_saveexec_b64 s[28:29], s[44:45]
	s_cbranch_execz .LBB0_1786
	v_or_b32_e32 v84, 32, v214
	v_ashrrev_i32_e32 v85, 31, v84
	v_readlane_b32 s14, v255, 48
	v_add_f32_e32 v86, v82, v83
	v_lshlrev_b64 v[82:83], 6, v[84:85]
	v_readlane_b32 s15, v255, 49
	s_lshl_b32 s80, s30, 2
	s_nop 0
	v_lshl_add_u64 v[82:83], s[14:15], 0, v[82:83]
	v_lshl_add_u64 v[82:83], s[0:1], 2, v[82:83]
	v_lshl_add_u64 v[82:83], v[82:83], 0, s[80:81]
	global_store_dword v[82:83], v86, off

; __device__ __forceinline__ unsigned cvtpk(float lo, float hi) { f32x2_t v = {lo, hi}; bf16x2_t b = __builtin_convertvector(v, bf16x2_t); return __builtin_bit_cast(unsigned, b); }
; __device__ __forceinline__ float bflo(unsigned u) { return __uint_as_float(u << 16); }
; __device__ __forceinline__ float bfhi(unsigned u) { return __uint_as_float(u & 0xffff0000u); }
;     __device__ __forceinline__ void operator()(const AccT& acc, const Unit& u, int wr, int wc, int fr, int fq) const {
;     ...
;             for (int m = 0; m < 4; ++m) { const int row = row0 + ai * 128 + m * 16; bf16_t* bp = bp0 + (size_t)(ai * 128 + m * 16) * DM; float q = 0.f;
; #pragma unroll
;                 for (int bj = 0; bj < 2; ++bj) { const u32x4 h4 = hv[ai][m][bj];
;                     f32x4 v0 = {bflo(h4.x), bfhi(h4.x), bflo(h4.y), bfhi(h4.y)}, v1 = {bflo(h4.z), bfhi(h4.z), bflo(h4.w), bfhi(h4.w)};
;                     v0 = v0 + acc[ai][bj][m][0] * c; v1 = v1 + acc[ai][bj][m][1] * c;
;                     q += ((v0[0] * v0[0] + v0[1] * v0[1]) + (v0[2] * v0[2] + v0[3] * v0[3])) + ((v1[0] * v1[0] + v1[1] * v1[1]) + (v1[2] * v1[2] + v1[3] * v1[3]));
;                     u32x4 w; w.x = cvtpk(v0[0], v0[1]); w.y = cvtpk(v0[2], v0[3]); w.z = cvtpk(v1[0], v1[1]); w.w = cvtpk(v1[2], v1[3]); *(u32x4*)(bp + bj * 128) = w; }
;                 q = xsum_16_32(q);
;                 if (fq == 0) ssn[(size_t)row * 16 + u.pn * 4 + wc] = q; }
.LBB0_2034:
	s_or_b64 exec, exec, s[28:29]
	v_lshlrev_b32_e32 v54, 16, v46
	v_and_b32_e32 v55, 0xffff0000, v46
	v_lshlrev_b32_e32 v46, 16, v47
	v_and_b32_e32 v47, 0xffff0000, v47
	v_lshlrev_b32_e32 v56, 16, v48
	v_and_b32_e32 v57, 0xffff0000, v48
	v_lshlrev_b32_e32 v48, 16, v49
	v_and_b32_e32 v49, 0xffff0000, v49
	v_pk_add_f32 v[60:61], v[168:169], v[46:47]
	v_pk_add_f32 v[46:47], v[166:167], v[54:55]
	v_pk_add_f32 v[54:55], v[164:165], v[48:49]
	v_pk_add_f32 v[48:49], v[162:163], v[56:57]
	v_mul_f32_e32 v56, v47, v47
	v_mul_f32_e32 v57, v61, v61
	v_fmac_f32_e32 v56, v46, v46
	v_fmac_f32_e32 v57, v60, v60
	s_mov_b64 s[14:15], 0x10000
	v_add_f32_e32 v56, v56, v57
	v_mul_f32_e32 v57, v49, v49
	v_lshl_add_u64 v[50:51], v[152:153], 0, s[14:15]
	v_fmac_f32_e32 v57, v48, v48
	v_cvt_pk_bf16_f32 v46, v46, v47
	v_cvt_pk_bf16_f32 v47, v60, v61
	v_cvt_pk_bf16_f32 v48, v48, v49
	v_cvt_pk_bf16_f32 v49, v54, v55
	global_store_dwordx4 v[50:51], v[46:49], off
	v_mul_f32_e32 v162, v55, v55
	v_fmac_f32_e32 v162, v54, v54
	v_lshlrev_b32_e32 v46, 16, v42
	v_and_b32_e32 v47, 0xffff0000, v42
	v_lshlrev_b32_e32 v42, 16, v43
	v_and_b32_e32 v43, 0xffff0000, v43
	v_lshlrev_b32_e32 v48, 16, v44
	v_and_b32_e32 v49, 0xffff0000, v44
	v_lshlrev_b32_e32 v44, 16, v45
	v_and_b32_e32 v45, 0xffff0000, v45
	v_pk_add_f32 v[50:51], v[160:161], v[42:43]
	v_pk_add_f32 v[42:43], v[158:159], v[46:47]
	v_pk_add_f32 v[46:47], v[156:157], v[44:45]
	v_pk_add_f32 v[44:45], v[154:155], v[48:49]
	v_mul_f32_e32 v48, v43, v43
	v_mul_f32_e32 v49, v51, v51
	v_fmac_f32_e32 v48, v42, v42
	v_fmac_f32_e32 v49, v50, v50
	v_add_f32_e32 v48, v48, v49
	v_mul_f32_e32 v49, v45, v45
	v_mul_f32_e32 v54, v47, v47
	v_fmac_f32_e32 v49, v44, v44
	v_fmac_f32_e32 v54, v46, v46
	v_add_f32_e32 v57, v57, v162
	v_add_f32_e32 v49, v49, v54
	s_mov_b64 s[14:15], 0x10100
	v_add_f32_e32 v56, v56, v57
	v_add_f32_e32 v48, v48, v49
	v_lshl_add_u64 v[52:53], v[152:153], 0, s[14:15]
	v_add_f32_e32 v48, v56, v48
	v_cvt_pk_bf16_f32 v42, v42, v43
	v_cvt_pk_bf16_f32 v43, v50, v51
	v_cvt_pk_bf16_f32 v44, v44, v45
	v_cvt_pk_bf16_f32 v45, v46, v47
	global_store_dwordx4 v[52:53], v[42:45], off
	s_nop 1
	v_mov_b32_e32 v42, v48
	s_nop 1
	v_permlane16_swap_b32_e32 v48, v42
	v_add_f32_e32 v42, v48, v42
	v_mov_b32_e32 v43, v42
	s_nop 1
	v_permlane32_swap_b32_e32 v42, v43
	s_and_saveexec_b64 s[28:29], s[38:39]
	s_cbranch_execz .LBB0_2036
	v_or_b32_e32 v44, 32, v206
	v_ashrrev_i32_e32 v45, 31, v44
	v_add_f32_e32 v46, v42, v43
	v_lshlrev_b64 v[42:43], 6, v[44:45]
	v_lshl_add_u64 v[42:43], s[22:23], 0, v[42:43]
	v_lshl_add_u64 v[42:43], s[0:1], 2, v[42:43]
	s_lshl_b32 s80, s30, 2
	v_lshl_add_u64 v[42:43], v[42:43], 0, s[80:81]
	global_store_dword v[42:43], v46, off
